# big-GEMM tile order panel groups 4,4,3,3,3 (N=1024 GEMMs 8,9)
# baseline (speedup 1.0000x reference)
.LBB0_154:
	s_cmp_ge_u32 s3, 120
	s_cbranch_scc1 .Lto_g1_a0
	s_sub_u32 s99, s3, 0
	s_lshr_b32 s98, s99, 2
	s_and_b32 s99, s99, 3
	s_branch .Lto_j_a0
.Lto_g1_a0:
	s_cmp_ge_u32 s3, 240
	s_cbranch_scc1 .Lto_g2_a0
	s_sub_u32 s99, s3, 120
	s_lshr_b32 s98, s99, 2
	s_and_b32 s99, s99, 3
	s_add_u32 s99, s99, 4
	s_branch .Lto_j_a0
.Lto_g2_a0:
	s_cmp_ge_u32 s3, 330
	s_cbranch_scc1 .Lto_g3_a0
	s_sub_u32 s99, s3, 240
	s_mul_hi_u32 s98, s99, 0xaaaaaaab
	s_lshr_b32 s98, s98, 1
	s_mul_i32 s100, s98, 3
	s_sub_u32 s99, s99, s100
	s_add_u32 s99, s99, 8
	s_branch .Lto_j_a0
.Lto_g3_a0:
	s_cmp_ge_u32 s3, 420
	s_cbranch_scc1 .Lto_g4_a0
	s_sub_u32 s99, s3, 330
	s_mul_hi_u32 s98, s99, 0xaaaaaaab
	s_lshr_b32 s98, s98, 1
	s_mul_i32 s100, s98, 3
	s_sub_u32 s99, s99, s100
	s_add_u32 s99, s99, 11
	s_branch .Lto_j_a0
.Lto_g4_a0:
	s_sub_u32 s99, s3, 420
	s_mul_hi_u32 s98, s99, 0xaaaaaaab
	s_lshr_b32 s98, s98, 1
	s_mul_i32 s100, s98, 3
	s_sub_u32 s99, s99, s100
	s_add_u32 s99, s99, 14

.LBB0_608:
	s_cmp_ge_u32 s3, 128
	s_cbranch_scc1 .Lto_g1_a1
	s_sub_u32 s99, s3, 0
	s_lshr_b32 s98, s99, 2
	s_and_b32 s99, s99, 3
	s_branch .Lto_j_a1
.Lto_g1_a1:
	s_cmp_ge_u32 s3, 256
	s_cbranch_scc1 .Lto_g2_a1
	s_sub_u32 s99, s3, 128
	s_lshr_b32 s98, s99, 2
	s_and_b32 s99, s99, 3
	s_add_u32 s99, s99, 4
	s_branch .Lto_j_a1
.Lto_g2_a1:
	s_cmp_ge_u32 s3, 352
	s_cbranch_scc1 .Lto_g3_a1
	s_sub_u32 s99, s3, 256
	s_mul_hi_u32 s98, s99, 0xaaaaaaab
	s_lshr_b32 s98, s98, 1
	s_mul_i32 s100, s98, 3
	s_sub_u32 s99, s99, s100
	s_add_u32 s99, s99, 8
	s_branch .Lto_j_a1
.Lto_g3_a1:
	s_cmp_ge_u32 s3, 448
	s_cbranch_scc1 .Lto_g4_a1
	s_sub_u32 s99, s3, 352
	s_mul_hi_u32 s98, s99, 0xaaaaaaab
	s_lshr_b32 s98, s98, 1
	s_mul_i32 s100, s98, 3
	s_sub_u32 s99, s99, s100
	s_add_u32 s99, s99, 11
	s_branch .Lto_j_a1
.Lto_g4_a1:
	s_sub_u32 s99, s3, 448
	s_mul_hi_u32 s98, s99, 0xaaaaaaab
	s_lshr_b32 s98, s98, 1
	s_mul_i32 s100, s98, 3
	s_sub_u32 s99, s99, s100
	s_add_u32 s99, s99, 14

.LBB0_882:
	s_cmp_ge_u32 s3, 176
	s_cbranch_scc1 .Lto_g1_a2
	s_sub_u32 s99, s3, 0
	s_lshr_b32 s98, s99, 2
	s_and_b32 s99, s99, 3
	s_branch .Lto_j_a2
.Lto_g1_a2:
	s_cmp_ge_u32 s3, 352
	s_cbranch_scc1 .Lto_g2_a2
	s_sub_u32 s99, s3, 176
	s_lshr_b32 s98, s99, 2
	s_and_b32 s99, s99, 3
	s_add_u32 s99, s99, 4
	s_branch .Lto_j_a2
.Lto_g2_a2:
	s_cmp_ge_u32 s3, 484
	s_cbranch_scc1 .Lto_g3_a2
	s_sub_u32 s99, s3, 352
	s_mul_hi_u32 s98, s99, 0xaaaaaaab
	s_lshr_b32 s98, s98, 1
	s_mul_i32 s100, s98, 3
	s_sub_u32 s99, s99, s100
	s_add_u32 s99, s99, 8
	s_branch .Lto_j_a2
.Lto_g3_a2:
	s_cmp_ge_u32 s3, 616
	s_cbranch_scc1 .Lto_g4_a2
	s_sub_u32 s99, s3, 484
	s_mul_hi_u32 s98, s99, 0xaaaaaaab
	s_lshr_b32 s98, s98, 1
	s_mul_i32 s100, s98, 3
	s_sub_u32 s99, s99, s100
	s_add_u32 s99, s99, 11
	s_branch .Lto_j_a2
.Lto_g4_a2:
	s_sub_u32 s99, s3, 616
	s_mul_hi_u32 s98, s99, 0xaaaaaaab
	s_lshr_b32 s98, s98, 1
	s_mul_i32 s100, s98, 3
	s_sub_u32 s99, s99, s100
	s_add_u32 s99, s99, 14
